# grid barrier spin loops: s_sleep 0 instead of s_sleep 1 (shorter poll interval)
# baseline (speedup 1.0000x reference)
.LBB0_1938:
	s_and_b32 s12, s17, 0xff
	s_mov_b64 s[10:11], -1
	s_cmp_lg_u32 s12, 0
	s_mov_b64 s[14:15], -1
	s_sleep 0
	s_cbranch_scc0 .LBB0_1941
	s_and_b64 vcc, exec, s[14:15]
	s_cbranch_vccz .LBB0_1937
